# ret_out (phase 4) V^T staging: same lane remap (4 adjacent lanes read 64 contiguous bytes of a row)
# speedup vs baseline: 1.0249x; 1.0058x over previous
.LBB0_186:
	s_andn2_b64 vcc, exec, s[4:5]
	s_cbranch_vccnz .LBB0_451
	s_cmp_lt_i32 s72, 3
	s_mov_b64 s[4:5], -1
	s_cbranch_scc1 .LBB0_385
	s_cmp_lt_i32 s72, 4
	s_cbranch_scc1 .LBB0_279
	v_writelane_b32 v254, s69, 63
	v_mov_b32_e32 v42, 0x260
	s_cmp_eq_u32 s72, 4
	s_cbranch_scc0 .LBB0_278
	v_bfe_u32 v44, v191, 2, 6
	v_and_b32_e32 v45, 3, v191
	v_lshl_or_b32 v44, v45, 6, v44
	v_and_b32_e32 v45, 0x100, v191
	v_or_b32_e32 v44, v44, v45
	v_add_u32_e32 v45, 0x200, v44
	v_add_u32_e32 v46, 0x400, v44
	v_add_u32_e32 v47, 0x600, v44
	v_ashrrev_i32_e32 v16, 31, v191
	v_lshrrev_b32_e32 v0, 28, v16
	v_add_u32_e32 v0, v191, v0
	v_ashrrev_i32_e32 v4, 4, v0
	v_and_b32_e32 v0, -16, v0
	s_movk_i32 s8, 0x1400
	s_movk_i32 s12, 0x110
	v_add_u32_e32 v18, 0x200, v191
	v_sub_u32_e32 v5, v191, v0
	v_mad_i64_i32 v[0:1], s[6:7], v4, s8, 0
	v_mul_lo_u32 v4, v4, s12
	v_ashrrev_i32_e32 v21, 31, v18
	v_add_u32_e32 v19, 0, v4
	v_lshrrev_b32_e32 v4, 28, v21
	v_add_u32_e32 v4, v18, v4
	v_ashrrev_i32_e32 v8, 4, v4
	v_and_b32_e32 v4, -16, v4
	v_add_u32_e32 v24, 0x400, v191
	v_lshlrev_b32_e32 v2, 3, v5
	v_lshlrev_b32_e32 v20, 4, v5
	v_sub_u32_e32 v9, v18, v4
	v_mad_i64_i32 v[4:5], s[6:7], v8, s8, 0
	v_mul_lo_u32 v8, v8, s12
	v_ashrrev_i32_e32 v25, 31, v24
	v_add_u32_e32 v22, 0, v8
	v_lshrrev_b32_e32 v8, 28, v25
	v_add_u32_e32 v8, v24, v8
	v_lshrrev_b32_e32 v16, 26, v16
	v_ashrrev_i32_e32 v12, 4, v8
	v_and_b32_e32 v8, -16, v8
	v_add_u32_e32 v28, 0x600, v191
	v_add_u32_e32 v16, v44, v16
	v_lshlrev_b32_e32 v6, 3, v9
	v_lshlrev_b32_e32 v23, 4, v9
	s_waitcnt lgkmcnt(0)
	v_sub_u32_e32 v13, v24, v8
	v_mad_i64_i32 v[8:9], s[6:7], v12, s8, 0
	v_mul_lo_u32 v12, v12, s12
	v_ashrrev_i32_e32 v29, 31, v28
	v_ashrrev_i32_e32 v32, 6, v16
	v_and_b32_e32 v16, 0xffffffc0, v16
	v_add_u32_e32 v26, 0, v12
	v_lshrrev_b32_e32 v12, 28, v29
	v_sub_u32_e32 v16, v44, v16
	v_readlane_b32 s4, v254, 59
	v_add_u32_e32 v12, v28, v12
	v_mul_i32_i24_e32 v78, 0x2800, v16
	v_lshlrev_b32_e32 v33, 2, v16
	v_lshrrev_b32_e32 v16, 26, v21
	s_lshl_b32 s4, s4, 11
	v_ashrrev_i32_e32 v30, 4, v12
	v_and_b32_e32 v12, -16, v12
	v_add_u32_e32 v16, v45, v16
	s_ashr_i32 s5, s4, 31
	v_lshlrev_b32_e32 v10, 3, v13
	v_lshlrev_b32_e32 v27, 4, v13
	v_sub_u32_e32 v31, v28, v12
	v_mad_i64_i32 v[12:13], s[6:7], v30, s8, 0
	v_ashrrev_i32_e32 v21, 6, v16
	v_and_b32_e32 v16, 0xffffffc0, v16
	s_add_i32 s0, 0, 0x22000
	s_lshl_b64 s[4:5], s[4:5], 2
	v_sub_u32_e32 v16, v45, v16
	s_movk_i32 s6, 0x2800
	s_add_u32 s4, s38, s4
	s_movk_i32 s7, 0x880
	v_mul_lo_u32 v82, v16, s6
	v_lshlrev_b32_e32 v34, 2, v16
	v_lshrrev_b32_e32 v16, 26, v25
	s_addc_u32 s5, s39, s5
	s_add_i32 s10, 0, 0x11000
	v_mul_lo_u32 v18, v21, s7
	v_add_u32_e32 v16, v46, v16
	v_lshlrev_b32_e32 v84, 3, v21
	v_add_u32_e32 v21, s10, v18
	v_ashrrev_i32_e32 v18, 6, v16
	v_and_b32_e32 v16, 0xffffffc0, v16
	v_sub_u32_e32 v16, v46, v16
	v_mul_lo_u32 v86, v16, s6
	v_lshlrev_b32_e32 v25, 2, v16
	v_lshrrev_b32_e32 v16, 26, v29
	v_lshlrev_b32_e32 v88, 3, v18
	v_mul_lo_u32 v18, v18, s7
	v_add_u32_e32 v16, v47, v16
	v_add_u32_e32 v24, s10, v18
	v_ashrrev_i32_e32 v18, 6, v16
	v_and_b32_e32 v16, 0xffffffc0, v16
	v_readlane_b32 s13, v254, 58
	v_and_b32_e32 v76, 15, v191
	v_sub_u32_e32 v16, v47, v16
	s_lshl_b32 s11, s13, 4
	v_mul_lo_u32 v90, v16, s6
	v_lshlrev_b32_e32 v92, 3, v18
	v_mul_lo_u32 v18, v18, s7
	v_lshlrev_b32_e32 v29, 2, v16
	v_or_b32_e32 v16, s11, v76
	v_add_u32_e32 v28, s10, v18
	v_lshrrev_b32_e32 v18, 4, v192
	v_mul_lo_u32 v16, v16, s12
	v_add_u32_e32 v36, 0, v16
	v_lshlrev_b32_e32 v16, 2, v18
	v_or_b32_e32 v37, s11, v16
	v_cmp_lt_i32_e64 s[14:15], v76, v37
	v_sub_u32_e32 v38, v76, v37
	v_cvt_f32_i32_e32 v103, v38
	v_writelane_b32 v255, s14, 10
	v_or_b32_e32 v38, 1, v37
	v_sub_u32_e32 v39, v76, v38
	v_writelane_b32 v255, s15, 11
	v_cmp_gt_i32_e64 s[14:15], v76, v37
	v_cvt_f32_i32_e32 v105, v39
	v_or_b32_e32 v39, 3, v37
	v_writelane_b32 v255, s14, 12
	v_or_b32_e32 v40, 2, v37
	v_or_b32_e32 v98, 16, v76
	v_writelane_b32 v255, s15, 13
	v_cmp_lt_i32_e64 s[14:15], v76, v39
	v_sub_u32_e32 v41, v76, v40
	v_cvt_f32_i32_e32 v107, v41
	v_writelane_b32 v255, s14, 14
	v_sub_u32_e32 v41, v76, v39
	v_or_b32_e32 v100, 32, v76
	v_writelane_b32 v255, s15, 15
	v_cmp_lt_i32_e64 s[14:15], v76, v40
	v_cvt_f32_i32_e32 v128, v41
	v_sub_u32_e32 v41, v98, v37
	v_writelane_b32 v255, s14, 16
	v_cvt_f32_i32_e32 v129, v41
	v_sub_u32_e32 v41, v98, v38
	v_writelane_b32 v255, s15, 17
	v_cmp_lt_i32_e64 s[14:15], v98, v37
	v_cvt_f32_i32_e32 v130, v41
	v_sub_u32_e32 v41, v98, v40
	v_writelane_b32 v255, s14, 18
	v_cvt_f32_i32_e32 v131, v41
	v_sub_u32_e32 v41, v98, v39
	v_writelane_b32 v255, s15, 19
	v_cmp_gt_i32_e64 s[14:15], v98, v37
	v_cvt_f32_i32_e32 v132, v41
	v_sub_u32_e32 v41, v100, v37
	v_writelane_b32 v255, s14, 20
	v_cvt_f32_i32_e32 v134, v41
	v_sub_u32_e32 v41, v100, v38
	v_writelane_b32 v255, s15, 21
	v_cmp_lt_i32_e64 s[14:15], v98, v39
	v_cvt_f32_i32_e32 v135, v41
	v_sub_u32_e32 v41, v100, v40
	v_writelane_b32 v255, s14, 22
	v_or_b32_e32 v94, 48, v192
	v_cvt_f32_i32_e32 v136, v41
	v_writelane_b32 v255, s15, 23
	v_cmp_lt_i32_e64 s[14:15], v98, v40
	v_sub_u32_e32 v41, v100, v39
	v_cvt_f32_i32_e32 v137, v41
	v_writelane_b32 v255, s14, 24
	v_sub_u32_e32 v41, v94, v37
	v_cvt_f32_i32_e32 v138, v41
	v_writelane_b32 v255, s15, 25
	v_cmp_lt_i32_e64 s[14:15], v100, v37
	v_sub_u32_e32 v41, v94, v38
	v_cvt_f32_i32_e32 v139, v41
	v_writelane_b32 v255, s14, 26
	v_sub_u32_e32 v41, v94, v40
	v_cvt_f32_i32_e32 v140, v41
	v_writelane_b32 v255, s15, 27
	v_cmp_gt_i32_e64 s[14:15], v100, v37
	v_sub_u32_e32 v41, v94, v39
	v_or_b32_e32 v102, 64, v76
	v_writelane_b32 v255, s14, 28
	v_cvt_f32_i32_e32 v141, v41
	v_sub_u32_e32 v41, v102, v37
	v_writelane_b32 v255, s15, 29
	v_cmp_lt_i32_e64 s[14:15], v100, v39
	v_cvt_f32_i32_e32 v142, v41
	v_sub_u32_e32 v41, v102, v38
	v_writelane_b32 v255, s14, 30
	v_cvt_f32_i32_e32 v143, v41
	v_sub_u32_e32 v41, v102, v40
	v_writelane_b32 v255, s15, 31
	v_cmp_lt_i32_e64 s[14:15], v100, v40
	v_cvt_f32_i32_e32 v144, v41
	v_sub_u32_e32 v41, v102, v39
	v_writelane_b32 v255, s14, 32
	v_or_b32_e32 v104, 0x50, v76
	s_cmp_lt_i32 s13, 1
	v_writelane_b32 v255, s15, 33
	v_cmp_lt_i32_e64 s[14:15], v94, v37
	v_cvt_f32_i32_e32 v145, v41
	v_sub_u32_e32 v41, v104, v37
	v_writelane_b32 v254, s14, 61
	v_lshlrev_b32_e32 v80, 3, v32
	v_mul_lo_u32 v32, v32, s7
	v_writelane_b32 v254, s15, 62
	v_cmp_gt_i32_e64 s[14:15], v94, v37
	s_cselect_b64 s[6:7], -1, 0
	s_cmp_lt_i32 s13, 2
	v_writelane_b32 v255, s14, 0
	v_cvt_f32_i32_e32 v146, v41
	v_sub_u32_e32 v41, v104, v38
	v_writelane_b32 v255, s15, 1
	v_cmp_lt_i32_e64 s[14:15], v94, v39
	s_cselect_b64 s[8:9], -1, 0
	s_cmp_lt_i32 s13, 3
	v_writelane_b32 v255, s14, 2
	v_cvt_f32_i32_e32 v147, v41
	v_sub_u32_e32 v41, v104, v40
	v_writelane_b32 v255, s15, 3
	v_cmp_lt_i32_e64 s[14:15], v94, v40
	s_cselect_b64 s[52:53], -1, 0
	s_cmp_lt_i32 s13, 4
	v_writelane_b32 v255, s14, 4
	v_cvt_f32_i32_e32 v148, v41
	v_sub_u32_e32 v41, v104, v39
	v_writelane_b32 v255, s15, 5
	v_cmp_lt_i32_e64 s[14:15], v102, v37
	v_or_b32_e32 v106, 0x60, v76
	s_cselect_b64 s[54:55], -1, 0
	v_writelane_b32 v255, s14, 6
	s_cmp_lt_i32 s13, 5
	v_cvt_f32_i32_e32 v149, v41
	v_writelane_b32 v255, s15, 7
	v_cmp_gt_i32_e64 s[14:15], v102, v37
	v_sub_u32_e32 v41, v106, v37
	s_cselect_b64 s[78:79], -1, 0
	v_writelane_b32 v255, s14, 8
	s_cmp_lt_i32 s13, 6
	v_cvt_f32_i32_e32 v150, v41
	v_writelane_b32 v255, s15, 9
	v_cmp_lt_i32_e64 s[14:15], v102, v39
	v_sub_u32_e32 v41, v106, v38
	s_cselect_b64 s[72:73], -1, 0
	v_writelane_b32 v255, s14, 34
	s_cmp_lt_i32 s13, 7
	v_cvt_f32_i32_e32 v151, v41
	v_writelane_b32 v255, s15, 35
	v_cmp_lt_i32_e64 s[14:15], v102, v40
	v_sub_u32_e32 v41, v106, v40
	s_cselect_b64 s[74:75], -1, 0
	s_cmp_lt_i32 s13, 8
	v_or_b32_e32 v96, 0x70, v192
	v_writelane_b32 v255, s14, 36
	v_cvt_f32_i32_e32 v158, v41
	v_sub_u32_e32 v41, v106, v39
	s_cselect_b64 s[76:77], -1, 0
	v_writelane_b32 v255, s15, 37
	v_cmp_lt_i32_e64 s[14:15], v104, v37
	v_cvt_f32_i32_e32 v159, v41
	v_sub_u32_e32 v41, v96, v37
	s_lshl_b32 s11, s13, 5
	v_writelane_b32 v255, s14, 38
	v_cvt_f32_i32_e32 v160, v41
	v_or_b32_e32 v41, s11, v76
	v_writelane_b32 v255, s15, 39
	v_cmp_gt_i32_e64 s[14:15], v104, v37
	v_mul_lo_u32 v41, v41, s12
	v_lshl_add_u32 v17, v192, 2, s0
	v_add_u32_e32 v32, s10, v32
	v_writelane_b32 v255, s14, 40
	v_add_u32_e32 v41, s10, v41
	s_lshl_b32 s10, s13, 9
	v_writelane_b32 v255, s15, 41
	v_cmp_lt_i32_e64 s[14:15], v104, v39
	v_add_u32_e32 v171, s10, v17
	v_sub_u32_e32 v17, v96, v39
	v_writelane_b32 v255, s14, 42
	v_cvt_f32_i32_e32 v172, v17
	v_lshlrev_b32_e32 v17, 7, v76
	v_writelane_b32 v255, s15, 43
	v_cmp_lt_i32_e64 s[14:15], v104, v40
	v_lshl_or_b32 v108, s13, 12, v17
	v_add_u32_e32 v17, 17, v76
	v_writelane_b32 v255, s14, 44
	v_cvt_f32_ubyte0_e32 v173, v17
	v_add_u32_e32 v17, 33, v76
	v_writelane_b32 v255, s15, 45
	v_cmp_lt_i32_e64 s[14:15], v106, v37
	v_cvt_f32_ubyte0_e32 v174, v17
	v_add_u32_e32 v17, 49, v76
	v_writelane_b32 v255, s14, 46
	v_cvt_f32_ubyte0_e32 v175, v17
	v_add_u32_e32 v17, 0x41, v76
	v_lshl_add_u32 v101, v37, 1, 0
	v_writelane_b32 v255, s15, 47
	v_cmp_gt_i32_e64 s[14:15], v106, v37
	v_cmp_lt_i32_e64 s[88:89], v96, v37
	v_cmp_gt_i32_e64 s[90:91], v96, v37
	v_sub_u32_e32 v37, v96, v38
	v_cvt_f32_ubyte0_e32 v176, v17
	v_add_u32_e32 v17, 0x51, v76
	v_cvt_f32_i32_e32 v161, v37
	v_sub_u32_e32 v37, v96, v40
	v_cvt_f32_ubyte0_e32 v177, v17
	v_add_u32_e32 v17, 0x61, v76
	v_cvt_f32_i32_e32 v162, v37
	v_cvt_f32_ubyte0_e32 v178, v17
	v_add_u32_e32 v17, 0x71, v76
	v_lshlrev_b32_e32 v14, 3, v31
	v_mul_lo_u32 v30, v30, s12
	v_or_b32_e32 v16, s11, v16
	v_cvt_f32_ubyte0_e32 v179, v17
	v_add_u32_e32 v17, 1, v76
	v_ashrrev_i32_e32 v3, 31, v2
	v_ashrrev_i32_e32 v7, 31, v6
	v_ashrrev_i32_e32 v11, 31, v10
	v_ashrrev_i32_e32 v15, 31, v14
	v_add_u32_e32 v30, 0, v30
	v_lshlrev_b32_e32 v31, 4, v31
	v_and_b32_e32 v35, 48, v191
	v_writelane_b32 v255, s14, 48
	v_lshlrev_b32_e32 v18, 3, v18
	v_cvt_f32_ubyte0_e32 v180, v17
	v_ashrrev_i32_e32 v17, 31, v16
	v_ashrrev_i32_e32 v79, 31, v78
	v_ashrrev_i32_e32 v81, 31, v80
	v_ashrrev_i32_e32 v83, 31, v82
	v_ashrrev_i32_e32 v85, 31, v84
	v_ashrrev_i32_e32 v87, 31, v86
	v_ashrrev_i32_e32 v89, 31, v88
	v_ashrrev_i32_e32 v91, 31, v90
	v_ashrrev_i32_e32 v93, 31, v92
	v_add_u32_e32 v77, 0, v35
	v_mul_u32_u24_e32 v95, 0x110, v76
	v_mul_u32_u24_e32 v97, 0x110, v94
	v_mul_u32_u24_e32 v99, 0x110, v96
	v_mul_u32_u24_e32 v133, 0x110, v98
	v_writelane_b32 v255, s15, 49
	v_cmp_lt_i32_e64 s[84:85], v106, v39
	v_cmp_lt_i32_e64 s[86:87], v106, v40
	v_lshl_add_u32 v163, v76, 2, s0
	v_lshl_add_u32 v164, v98, 2, s0
	v_lshl_add_u32 v165, v100, 2, s0
	v_lshl_add_u32 v166, v94, 2, s0
	v_lshl_add_u32 v167, v102, 2, s0
	v_lshl_add_u32 v168, v104, 2, s0
	v_lshl_add_u32 v169, v106, 2, s0
	v_lshl_add_u32 v170, v96, 2, s0
	v_cmp_lt_i32_e64 s[92:93], v96, v39
	v_ashrrev_i32_e32 v109, 31, v108
	v_lshlrev_b64 v[110:111], 1, v[0:1]
	v_lshlrev_b64 v[112:113], 1, v[2:3]
	v_add_u32_e32 v181, v19, v20
	v_lshlrev_b64 v[114:115], 1, v[4:5]
	v_lshlrev_b64 v[116:117], 1, v[6:7]
	v_add_u32_e32 v193, v22, v23
	v_lshlrev_b64 v[118:119], 1, v[8:9]
	v_lshlrev_b64 v[120:121], 1, v[10:11]
	v_add_u32_e32 v194, v26, v27
	v_lshlrev_b64 v[122:123], 1, v[12:13]
	v_lshlrev_b64 v[124:125], 1, v[14:15]
	v_add_u32_e32 v195, v30, v31
	v_add_u32_e32 v196, v32, v33
	v_add_u32_e32 v197, v21, v34
	v_add_u32_e32 v198, v24, v25
	v_add_u32_e32 v199, v28, v29
	v_lshlrev_b32_e32 v152, 1, v18
	v_add_u32_e32 v200, v41, v35
	v_lshlrev_b64 v[126:127], 1, v[16:17]
	v_add_u32_e32 v201, v36, v35
	v_cmp_lt_i32_e64 s[94:95], v96, v40
	v_cmp_gt_u32_e64 s[96:97], 16, v192
	s_branch .LBB0_193
